# baseline (speedup 1.0000x reference)
; #define PEER_LOADREC_FROM(isrc_, lb_) do { \
;         _Pragma("unroll") for (int q_ = 0; q_ < 8; ++q_) { \
;             const int ia_ = __builtin_amdgcn_readlane(isrc_, (lb_) + 2 * q_), ib_ = __builtin_amdgcn_readlane(isrc_, (lb_) + 2 * q_ + 1); \
;             ra[q_] = *(const u32x4*)(REC + (size_t)ia_ * 1024); rb[q_] = *(const u32x4*)(REC + (size_t)ib_ * 1024); } } while (0)
; #define PEER_SWAP() do { _Pragma("unroll") for (int q_ = 0; q_ < 8; ++q_) _Pragma("unroll") for (int c_ = 0; c_ < 4; ++c_) { \
;             const auto r_ = __builtin_amdgcn_permlane32_swap(ra[q_][c_], rb[q_][c_], false, false); ucur[q_][c_] = r_[0]; vcur[q_][c_] = r_[1]; } } while (0)
; #define PEER_LOADREC_MEM(ep_) do { \
;         _Pragma("unroll") for (int q_ = 0; q_ < 8; ++q_) { \
;             const int ia_ = __builtin_amdgcn_readfirstlane((ep_)[2 * q_]), ib_ = __builtin_amdgcn_readfirstlane((ep_)[2 * q_ + 1]); \
;             ra[q_] = *(const u32x4*)(REC + (size_t)ia_ * 1024); rb[q_] = *(const u32x4*)(REC + (size_t)ib_ * 1024); } } while (0)
; DI void peer_phase(const Params& p, int layer, bool dry) {
;     ...
;     if (gw < T_TOK) {
;         PEER_LOADREC_MEM(eidx + (size_t)gw * 128);
;         PEER_SWAP();
;     }
;     u32x4 xq[4]; int ivq0 = 0, ivq1 = 0; float gvq0 = 0.f, gvq1 = 0.f;
;     ...
;         for (int bt = 0; bt < 8; ++bt) {
;             if (bt < 7) { const int nb = bt + 1; const int isrc = (nb < 4) ? iv0 : iv1; const int lb = (nb & 3) * 16; PEER_LOADREC_FROM(isrc, lb); }
;             else PEER_LOADREC_MEM(eidx + (size_t)tn * 128);
;             const int myidx = __shfl((bt < 4) ? iv0 : iv1, (bt & 3) * 16 + esel16);
;             const float gsc = __shfl((bt < 4) ? gv0 : gv1, (bt & 3) * 16 + esel16) * SV[myidx], usc = SU[myidx];
.LBB0_38:
	s_andn2_b64 vcc, exec, s[72:73]
	s_cbranch_vccnz .LBB0_35
	v_lshlrev_b32_e32 v70, 2, v96
	s_add_u32 s40, s76, s0
	s_addc_u32 s41, s77, s1
	global_load_dword v218, v70, s[24:25]
	global_load_dword v98, v70, s[24:25] offset:256
	global_load_dword v226, v70, s[40:41]
	global_load_dword v99, v70, s[40:41] offset:256
	s_mov_b32 s60, 48
	s_movk_i32 s21, 0x80
	s_waitcnt vmcnt(0)
	v_lshrrev_b32_e32 v64, 11, v218
	v_lshrrev_b32_e32 v65, 11, v98
	s_bfe_u32 s34, s22, 0x1000b
	s_mul_i32 s34, s34, 7
	s_nop 0
	v_xor_b32_e32 v64, s34, v64
	v_xor_b32_e32 v65, s34, v65
	s_mov_b32 s36, 0
	v_cmp_eq_u32_e64 s[28:29], 0, v64
	v_cmp_eq_u32_e64 s[30:31], 0, v65
	s_bcnt1_i32_b64 s34, s[28:29]
	s_bcnt1_i32_b64 s35, s[30:31]
	v_mbcnt_lo_u32_b32 v68, s28, 0
	v_mbcnt_hi_u32_b32 v68, s29, v68
	v_mbcnt_lo_u32_b32 v69, s30, 0
	v_mbcnt_hi_u32_b32 v69, s31, v69
	v_add_u32_e32 v68, s36, v68
	s_add_i32 s36, s36, s34
	v_add_u32_e32 v69, s36, v69
	s_add_i32 s36, s36, s35
	v_cndmask_b32_e64 v66, v66, v68, s[28:29]
	v_cndmask_b32_e64 v67, v67, v69, s[30:31]
	v_cmp_eq_u32_e64 s[28:29], 1, v64
	v_cmp_eq_u32_e64 s[30:31], 1, v65
	s_bcnt1_i32_b64 s34, s[28:29]
	s_bcnt1_i32_b64 s35, s[30:31]
	v_mbcnt_lo_u32_b32 v68, s28, 0
	v_mbcnt_hi_u32_b32 v68, s29, v68
	v_mbcnt_lo_u32_b32 v69, s30, 0
	v_mbcnt_hi_u32_b32 v69, s31, v69
	v_add_u32_e32 v68, s36, v68
	s_add_i32 s36, s36, s34
	v_add_u32_e32 v69, s36, v69
	s_add_i32 s36, s36, s35
	v_cndmask_b32_e64 v66, v66, v68, s[28:29]
	v_cndmask_b32_e64 v67, v67, v69, s[30:31]
	v_cmp_eq_u32_e64 s[28:29], 2, v64
	v_cmp_eq_u32_e64 s[30:31], 2, v65
	s_bcnt1_i32_b64 s34, s[28:29]
	s_bcnt1_i32_b64 s35, s[30:31]
	v_mbcnt_lo_u32_b32 v68, s28, 0
	v_mbcnt_hi_u32_b32 v68, s29, v68
	v_mbcnt_lo_u32_b32 v69, s30, 0
	v_mbcnt_hi_u32_b32 v69, s31, v69
	v_add_u32_e32 v68, s36, v68
	s_add_i32 s36, s36, s34
	v_add_u32_e32 v69, s36, v69
	s_add_i32 s36, s36, s35
	v_cndmask_b32_e64 v66, v66, v68, s[28:29]
	v_cndmask_b32_e64 v67, v67, v69, s[30:31]
	v_cmp_eq_u32_e64 s[28:29], 3, v64
	v_cmp_eq_u32_e64 s[30:31], 3, v65
	s_bcnt1_i32_b64 s34, s[28:29]
	s_bcnt1_i32_b64 s35, s[30:31]
	v_mbcnt_lo_u32_b32 v68, s28, 0
	v_mbcnt_hi_u32_b32 v68, s29, v68
	v_mbcnt_lo_u32_b32 v69, s30, 0
	v_mbcnt_hi_u32_b32 v69, s31, v69
	v_add_u32_e32 v68, s36, v68
	s_add_i32 s36, s36, s34
	v_add_u32_e32 v69, s36, v69
	s_add_i32 s36, s36, s35
	v_cndmask_b32_e64 v66, v66, v68, s[28:29]
	v_cndmask_b32_e64 v67, v67, v69, s[30:31]
	v_cmp_eq_u32_e64 s[28:29], 4, v64
	v_cmp_eq_u32_e64 s[30:31], 4, v65
	s_bcnt1_i32_b64 s34, s[28:29]
	s_bcnt1_i32_b64 s35, s[30:31]
	v_mbcnt_lo_u32_b32 v68, s28, 0
	v_mbcnt_hi_u32_b32 v68, s29, v68
	v_mbcnt_lo_u32_b32 v69, s30, 0
	v_mbcnt_hi_u32_b32 v69, s31, v69
	v_add_u32_e32 v68, s36, v68
	s_add_i32 s36, s36, s34
	v_add_u32_e32 v69, s36, v69
	s_add_i32 s36, s36, s35
	v_cndmask_b32_e64 v66, v66, v68, s[28:29]
	v_cndmask_b32_e64 v67, v67, v69, s[30:31]
	v_cmp_eq_u32_e64 s[28:29], 5, v64
	v_cmp_eq_u32_e64 s[30:31], 5, v65
	s_bcnt1_i32_b64 s34, s[28:29]
	s_bcnt1_i32_b64 s35, s[30:31]
	v_mbcnt_lo_u32_b32 v68, s28, 0
	v_mbcnt_hi_u32_b32 v68, s29, v68
	v_mbcnt_lo_u32_b32 v69, s30, 0
	v_mbcnt_hi_u32_b32 v69, s31, v69
	v_add_u32_e32 v68, s36, v68
	s_add_i32 s36, s36, s34
	v_add_u32_e32 v69, s36, v69
	s_add_i32 s36, s36, s35
	v_cndmask_b32_e64 v66, v66, v68, s[28:29]
	v_cndmask_b32_e64 v67, v67, v69, s[30:31]
	v_cmp_eq_u32_e64 s[28:29], 6, v64
	v_cmp_eq_u32_e64 s[30:31], 6, v65
	s_bcnt1_i32_b64 s34, s[28:29]
	s_bcnt1_i32_b64 s35, s[30:31]
	v_mbcnt_lo_u32_b32 v68, s28, 0
	v_mbcnt_hi_u32_b32 v68, s29, v68
	v_mbcnt_lo_u32_b32 v69, s30, 0
	v_mbcnt_hi_u32_b32 v69, s31, v69
	v_add_u32_e32 v68, s36, v68
	s_add_i32 s36, s36, s34
	v_add_u32_e32 v69, s36, v69
	s_add_i32 s36, s36, s35
	v_cndmask_b32_e64 v66, v66, v68, s[28:29]
	v_cndmask_b32_e64 v67, v67, v69, s[30:31]
	v_cmp_eq_u32_e64 s[28:29], 7, v64
	v_cmp_eq_u32_e64 s[30:31], 7, v65
	s_bcnt1_i32_b64 s34, s[28:29]
	s_bcnt1_i32_b64 s35, s[30:31]
	v_mbcnt_lo_u32_b32 v68, s28, 0
	v_mbcnt_hi_u32_b32 v68, s29, v68
	v_mbcnt_lo_u32_b32 v69, s30, 0
	v_mbcnt_hi_u32_b32 v69, s31, v69
	v_add_u32_e32 v68, s36, v68
	s_add_i32 s36, s36, s34
	v_add_u32_e32 v69, s36, v69
	s_add_i32 s36, s36, s35
	v_cndmask_b32_e64 v66, v66, v68, s[28:29]
	v_cndmask_b32_e64 v67, v67, v69, s[30:31]
	v_lshl_add_u32 v71, v66, 2, s32
	v_lshl_add_u32 v72, v67, 2, s32
	v_lshl_add_u32 v70, v96, 2, s32
	ds_write_b32 v71, v218
	ds_write_b32 v72, v98
	ds_write_b32 v71, v226 offset:512
	ds_write_b32 v72, v99 offset:512
	s_waitcnt lgkmcnt(0)
	ds_read_b32 v218, v70
	ds_read_b32 v98, v70 offset:256
	ds_read_b32 v226, v70 offset:512
	ds_read_b32 v99, v70 offset:768
	s_waitcnt lgkmcnt(0)
	v_readlane_b32 s28, v218, 0
	v_readlane_b32 s26, v218, 1
	v_readlane_b32 s30, v218, 2
	v_readlane_b32 s40, v218, 3
	v_readlane_b32 s34, v218, 4
	v_readlane_b32 s38, v218, 5
	v_readlane_b32 s50, v218, 6
	v_readlane_b32 s48, v218, 7
	v_readlane_b32 s54, v218, 8
	v_readlane_b32 s46, v218, 9
	v_readlane_b32 s58, v218, 10
	v_readlane_b32 s36, v218, 11
	v_readlane_b32 s62, v218, 12
	v_readlane_b32 s52, v218, 13
	v_readlane_b32 s64, v218, 14
	v_readlane_b32 s56, v218, 15
	s_branch .LBB0_35
